# WIN GEMM: padded unit pn=19 skips the MFMA blocks whose accumulators are never stored (bj=1 all waves, bj=0 column waves 1-3)
# baseline (speedup 1.0000x reference)
.LBB0_403:
	s_cmp_eq_u32 s78, 19
	s_cselect_b32 vcc_hi, 1, 0
	v_readlane_b32 vcc_lo, v252, 19
	s_and_b32 vcc_lo, vcc_lo, 0xc0
	s_cmp_lg_u32 vcc_lo, 0
	s_cselect_b32 vcc_lo, vcc_hi, 0
	s_add_u32 s66, s64, 0xfffc0080
	s_addc_u32 s67, s65, -1
	s_add_i32 s75, 0, 0x10000
	s_cmp_eq_u32 s74, 12
	s_cselect_b32 s69, s59, s67
	s_cselect_b32 s68, s70, s66
	v_add_u32_e32 v0, s75, v169
	s_cselect_b32 s67, s57, s73
	s_cselect_b32 s66, s71, s72
	s_add_i32 s79, 0, 0x14000
	ds_read_b128 v[134:137], v0
	ds_read_b128 v[138:141], v0 offset:1024
	ds_read_b128 v[142:145], v0 offset:2048
	ds_read_b128 v[146:149], v0 offset:3072
	v_add_u32_e32 v0, s79, v169
	ds_read_b128 v[150:153], v0
	ds_read_b128 v[154:157], v0 offset:1024
	ds_read_b128 v[158:161], v0 offset:2048
	ds_read_b128 v[162:165], v0 offset:3072
	s_add_i32 m0, s9, 0xc000
	ds_read_b128 v[182:185], v171
	ds_read_b128 v[186:189], v171 offset:1024
	ds_read_b128 v[190:193], v171 offset:2048
	ds_read_b128 v[194:197], v171 offset:3072
	ds_read_b128 v[208:211], v171 offset:4096
	ds_read_b128 v[212:215], v171 offset:5120
	ds_read_b128 v[216:219], v171 offset:6144
	ds_read_b128 v[232:235], v171 offset:7168
	global_load_lds_dwordx4 v180, s[64:65]
	s_add_i32 m0, s9, 0xe000
	s_nop 0
	global_load_lds_dwordx4 v178, s[64:65]
	s_waitcnt vmcnt(8)
	s_waitcnt lgkmcnt(0)
	s_barrier
	s_setprio 1
	s_waitcnt lgkmcnt(0)
	s_cmp_lg_u32 vcc_lo, 0
	s_cbranch_scc1 .Lwinskip_0
	v_mfma_f32_16x16x32_bf16 v[130:133], v[134:137], v[182:185], v[130:133]
	v_mfma_f32_16x16x32_bf16 v[126:129], v[142:145], v[182:185], v[126:129]
	v_mfma_f32_16x16x32_bf16 v[122:125], v[134:137], v[190:193], v[122:125]
	v_mfma_f32_16x16x32_bf16 v[118:121], v[142:145], v[190:193], v[118:121]
	v_mfma_f32_16x16x32_bf16 v[114:117], v[134:137], v[208:211], v[114:117]
	v_mfma_f32_16x16x32_bf16 v[110:113], v[142:145], v[208:211], v[110:113]
	v_mfma_f32_16x16x32_bf16 v[106:109], v[134:137], v[216:219], v[106:109]
	v_mfma_f32_16x16x32_bf16 v[102:105], v[142:145], v[216:219], v[102:105]
	v_mfma_f32_16x16x32_bf16 v[130:133], v[138:141], v[186:189], v[130:133]
	v_mfma_f32_16x16x32_bf16 v[126:129], v[146:149], v[186:189], v[126:129]
	v_mfma_f32_16x16x32_bf16 v[122:125], v[138:141], v[194:197], v[122:125]
	v_mfma_f32_16x16x32_bf16 v[118:121], v[146:149], v[194:197], v[118:121]
	v_mfma_f32_16x16x32_bf16 v[114:117], v[138:141], v[212:215], v[114:117]
	v_mfma_f32_16x16x32_bf16 v[110:113], v[146:149], v[212:215], v[110:113]
	v_mfma_f32_16x16x32_bf16 v[106:109], v[138:141], v[232:235], v[106:109]
	v_mfma_f32_16x16x32_bf16 v[102:105], v[146:149], v[232:235], v[102:105]
.Lwinskip_0:
	s_setprio 0
	s_setprio 1
	s_cmp_lg_u32 vcc_hi, 0
	s_cbranch_scc1 .Lwinskip_1
	v_mfma_f32_16x16x32_bf16 v[62:65], v[150:153], v[182:185], v[62:65]
	v_mfma_f32_16x16x32_bf16 v[58:61], v[158:161], v[182:185], v[58:61]
	v_mfma_f32_16x16x32_bf16 v[54:57], v[150:153], v[190:193], v[54:57]
	v_mfma_f32_16x16x32_bf16 v[50:53], v[158:161], v[190:193], v[50:53]
	v_mfma_f32_16x16x32_bf16 v[46:49], v[150:153], v[208:211], v[46:49]
	v_mfma_f32_16x16x32_bf16 v[42:45], v[158:161], v[208:211], v[42:45]
	v_mfma_f32_16x16x32_bf16 v[38:41], v[150:153], v[216:219], v[38:41]
	v_mfma_f32_16x16x32_bf16 v[34:37], v[158:161], v[216:219], v[34:37]
	v_mfma_f32_16x16x32_bf16 v[62:65], v[154:157], v[186:189], v[62:65]
	v_mfma_f32_16x16x32_bf16 v[58:61], v[162:165], v[186:189], v[58:61]
	v_mfma_f32_16x16x32_bf16 v[54:57], v[154:157], v[194:197], v[54:57]
	v_mfma_f32_16x16x32_bf16 v[50:53], v[162:165], v[194:197], v[50:53]
	v_mfma_f32_16x16x32_bf16 v[46:49], v[154:157], v[212:215], v[46:49]
	v_mfma_f32_16x16x32_bf16 v[42:45], v[162:165], v[212:215], v[42:45]
	v_mfma_f32_16x16x32_bf16 v[38:41], v[154:157], v[232:235], v[38:41]
	v_mfma_f32_16x16x32_bf16 v[34:37], v[162:165], v[232:235], v[34:37]
.Lwinskip_1:
	s_setprio 0
	s_barrier
	s_add_i32 s75, s75, s8
	s_mov_b32 m0, s75
	ds_read_b128 v[182:185], v171 offset:16384
	ds_read_b128 v[186:189], v171 offset:17408
	ds_read_b128 v[190:193], v171 offset:18432
	ds_read_b128 v[194:197], v171 offset:19456
	ds_read_b128 v[208:211], v171 offset:20480
	ds_read_b128 v[212:215], v171 offset:21504
	ds_read_b128 v[216:219], v171 offset:22528
	ds_read_b128 v[232:235], v171 offset:23552
	global_load_lds_dwordx4 v166, s[66:67]
	s_add_i32 m0, s75, 0x2000
	s_add_u32 s76, s66, 0x40000
	s_addc_u32 s77, s67, 0
	s_add_i32 s75, s79, s8
	global_load_lds_dwordx4 v94, s[66:67]
	s_mov_b32 m0, s75
	s_nop 0
	global_load_lds_dwordx4 v166, s[76:77]
	s_add_i32 m0, s75, 0x2000
	s_nop 0
	global_load_lds_dwordx4 v94, s[76:77]
	s_mov_b32 m0, s9
	s_nop 0
	global_load_lds_dwordx4 v166, s[68:69]
	s_mov_b32 m0, s12
	s_nop 0
	global_load_lds_dwordx4 v94, s[68:69]
	s_waitcnt vmcnt(8)
	s_waitcnt lgkmcnt(0)
	s_barrier
	s_setprio 1
	s_waitcnt lgkmcnt(0)
	s_cmp_lg_u32 vcc_lo, 0
	s_cbranch_scc1 .Lwinskip_2
	v_mfma_f32_16x16x32_bf16 v[98:101], v[134:137], v[182:185], v[98:101]
	v_mfma_f32_16x16x32_bf16 v[90:93], v[142:145], v[182:185], v[90:93]
	v_mfma_f32_16x16x32_bf16 v[86:89], v[134:137], v[190:193], v[86:89]
	v_mfma_f32_16x16x32_bf16 v[82:85], v[142:145], v[190:193], v[82:85]
	v_mfma_f32_16x16x32_bf16 v[78:81], v[134:137], v[208:211], v[78:81]
	v_mfma_f32_16x16x32_bf16 v[74:77], v[142:145], v[208:211], v[74:77]
	v_mfma_f32_16x16x32_bf16 v[70:73], v[134:137], v[216:219], v[70:73]
	v_mfma_f32_16x16x32_bf16 v[66:69], v[142:145], v[216:219], v[66:69]
	v_mfma_f32_16x16x32_bf16 v[98:101], v[138:141], v[186:189], v[98:101]
	v_mfma_f32_16x16x32_bf16 v[90:93], v[146:149], v[186:189], v[90:93]
	v_mfma_f32_16x16x32_bf16 v[86:89], v[138:141], v[194:197], v[86:89]
	v_mfma_f32_16x16x32_bf16 v[82:85], v[146:149], v[194:197], v[82:85]
	v_mfma_f32_16x16x32_bf16 v[78:81], v[138:141], v[212:215], v[78:81]
	v_mfma_f32_16x16x32_bf16 v[74:77], v[146:149], v[212:215], v[74:77]
	v_mfma_f32_16x16x32_bf16 v[70:73], v[138:141], v[232:235], v[70:73]
	v_mfma_f32_16x16x32_bf16 v[66:69], v[146:149], v[232:235], v[66:69]
.Lwinskip_2:
	s_setprio 0
	s_setprio 1
	s_cmp_lg_u32 vcc_hi, 0
	s_cbranch_scc1 .Lwinskip_3
	v_mfma_f32_16x16x32_bf16 v[30:33], v[150:153], v[182:185], v[30:33]
	v_mfma_f32_16x16x32_bf16 v[26:29], v[158:161], v[182:185], v[26:29]
	v_mfma_f32_16x16x32_bf16 v[22:25], v[150:153], v[190:193], v[22:25]
	v_mfma_f32_16x16x32_bf16 v[18:21], v[158:161], v[190:193], v[18:21]
	v_mfma_f32_16x16x32_bf16 v[14:17], v[150:153], v[208:211], v[14:17]
	v_mfma_f32_16x16x32_bf16 v[10:13], v[158:161], v[208:211], v[10:13]
	v_mfma_f32_16x16x32_bf16 v[6:9], v[150:153], v[216:219], v[6:9]
	v_mfma_f32_16x16x32_bf16 v[2:5], v[158:161], v[216:219], v[2:5]
	v_mfma_f32_16x16x32_bf16 v[30:33], v[154:157], v[186:189], v[30:33]
	v_mfma_f32_16x16x32_bf16 v[26:29], v[162:165], v[186:189], v[26:29]
	v_mfma_f32_16x16x32_bf16 v[22:25], v[154:157], v[194:197], v[22:25]
	v_mfma_f32_16x16x32_bf16 v[18:21], v[162:165], v[194:197], v[18:21]
	v_mfma_f32_16x16x32_bf16 v[14:17], v[154:157], v[212:215], v[14:17]
	v_mfma_f32_16x16x32_bf16 v[10:13], v[162:165], v[212:215], v[10:13]
	v_mfma_f32_16x16x32_bf16 v[6:9], v[154:157], v[232:235], v[6:9]
	v_mfma_f32_16x16x32_bf16 v[2:5], v[162:165], v[232:235], v[2:5]
.Lwinskip_3:
	s_setprio 0
	s_barrier
	s_add_i32 s75, 0, 0x18000
	v_add_u32_e32 v0, s75, v169
	s_add_i32 s76, 0, 0x1c000
	ds_read_b128 v[134:137], v0
	ds_read_b128 v[138:141], v0 offset:1024
	ds_read_b128 v[142:145], v0 offset:2048
	ds_read_b128 v[146:149], v0 offset:3072
	v_add_u32_e32 v0, s76, v169
	ds_read_b128 v[150:153], v0
	ds_read_b128 v[154:157], v0 offset:1024
	ds_read_b128 v[158:161], v0 offset:2048
	ds_read_b128 v[162:165], v0 offset:3072
	s_add_u32 s68, s68, 0x40000
	s_addc_u32 s69, s69, 0
	s_mov_b32 m0, s13
	ds_read_b128 v[182:185], v171 offset:32768
	ds_read_b128 v[186:189], v171 offset:33792
	ds_read_b128 v[190:193], v171 offset:34816
	ds_read_b128 v[194:197], v171 offset:35840
	ds_read_b128 v[208:211], v171 offset:36864
	ds_read_b128 v[212:215], v171 offset:37888
	ds_read_b128 v[216:219], v171 offset:38912
	ds_read_b128 v[232:235], v171 offset:39936
	global_load_lds_dwordx4 v166, s[68:69]
	s_mov_b32 m0, s25
	s_nop 0
	global_load_lds_dwordx4 v94, s[68:69]
	s_waitcnt vmcnt(8)
	s_waitcnt lgkmcnt(0)
	s_barrier
	s_setprio 1
	s_waitcnt lgkmcnt(0)
	s_cmp_lg_u32 vcc_lo, 0
	s_cbranch_scc1 .Lwinskip_4
	v_mfma_f32_16x16x32_bf16 v[130:133], v[134:137], v[182:185], v[130:133]
	v_mfma_f32_16x16x32_bf16 v[126:129], v[142:145], v[182:185], v[126:129]
	v_mfma_f32_16x16x32_bf16 v[122:125], v[134:137], v[190:193], v[122:125]
	v_mfma_f32_16x16x32_bf16 v[118:121], v[142:145], v[190:193], v[118:121]
	v_mfma_f32_16x16x32_bf16 v[114:117], v[134:137], v[208:211], v[114:117]
	v_mfma_f32_16x16x32_bf16 v[110:113], v[142:145], v[208:211], v[110:113]
	v_mfma_f32_16x16x32_bf16 v[106:109], v[134:137], v[216:219], v[106:109]
	v_mfma_f32_16x16x32_bf16 v[102:105], v[142:145], v[216:219], v[102:105]
	v_mfma_f32_16x16x32_bf16 v[130:133], v[138:141], v[186:189], v[130:133]
	v_mfma_f32_16x16x32_bf16 v[126:129], v[146:149], v[186:189], v[126:129]
	v_mfma_f32_16x16x32_bf16 v[122:125], v[138:141], v[194:197], v[122:125]
	v_mfma_f32_16x16x32_bf16 v[118:121], v[146:149], v[194:197], v[118:121]
	v_mfma_f32_16x16x32_bf16 v[114:117], v[138:141], v[212:215], v[114:117]
	v_mfma_f32_16x16x32_bf16 v[110:113], v[146:149], v[212:215], v[110:113]
	v_mfma_f32_16x16x32_bf16 v[106:109], v[138:141], v[232:235], v[106:109]
	v_mfma_f32_16x16x32_bf16 v[102:105], v[146:149], v[232:235], v[102:105]

.Lwinskip_5:
	s_setprio 0
	s_barrier
	s_add_i32 s79, s75, s8
	s_add_i32 m0, s79, 0xffffff80
	ds_read_b128 v[182:185], v171 offset:49152
	ds_read_b128 v[186:189], v171 offset:50176
	ds_read_b128 v[190:193], v171 offset:51200
	ds_read_b128 v[194:197], v171 offset:52224
	ds_read_b128 v[208:211], v171 offset:53248
	ds_read_b128 v[212:215], v171 offset:54272
	ds_read_b128 v[216:219], v171 offset:55296
	ds_read_b128 v[232:235], v171 offset:56320
	global_load_lds_dwordx4 v166, s[66:67] offset:128
	s_add_i32 m0, s79, 0x1f80
	s_nop 0
	global_load_lds_dwordx4 v94, s[66:67] offset:128
	s_add_i32 s79, s76, s8
	s_add_u32 s66, s66, 0x40080
	s_addc_u32 s67, s67, 0
	s_mov_b32 m0, s79
	s_nop 0
	global_load_lds_dwordx4 v166, s[66:67]
	s_add_i32 m0, s79, 0x2000
	s_nop 0
	global_load_lds_dwordx4 v94, s[66:67]
	s_add_u32 s68, s68, 0xfffc0080
	s_addc_u32 s69, s69, -1
	s_mov_b32 m0, s33
	s_nop 0
	global_load_lds_dwordx4 v166, s[68:69]
	s_mov_b32 m0, s80
	s_nop 0
	global_load_lds_dwordx4 v94, s[68:69]
	s_waitcnt vmcnt(8)
	s_waitcnt lgkmcnt(0)
	s_barrier
	s_setprio 1
	s_waitcnt lgkmcnt(0)
	s_cmp_lg_u32 vcc_lo, 0
	s_cbranch_scc1 .Lwinskip_6
	v_mfma_f32_16x16x32_bf16 v[98:101], v[134:137], v[182:185], v[98:101]
	v_mfma_f32_16x16x32_bf16 v[90:93], v[142:145], v[182:185], v[90:93]
	v_mfma_f32_16x16x32_bf16 v[86:89], v[134:137], v[190:193], v[86:89]
	v_mfma_f32_16x16x32_bf16 v[82:85], v[142:145], v[190:193], v[82:85]
	v_mfma_f32_16x16x32_bf16 v[78:81], v[134:137], v[208:211], v[78:81]
	v_mfma_f32_16x16x32_bf16 v[74:77], v[142:145], v[208:211], v[74:77]
	v_mfma_f32_16x16x32_bf16 v[70:73], v[134:137], v[216:219], v[70:73]
	v_mfma_f32_16x16x32_bf16 v[66:69], v[142:145], v[216:219], v[66:69]
	v_mfma_f32_16x16x32_bf16 v[98:101], v[138:141], v[186:189], v[98:101]
	v_mfma_f32_16x16x32_bf16 v[90:93], v[146:149], v[186:189], v[90:93]
	v_mfma_f32_16x16x32_bf16 v[86:89], v[138:141], v[194:197], v[86:89]
	v_mfma_f32_16x16x32_bf16 v[82:85], v[146:149], v[194:197], v[82:85]
	v_mfma_f32_16x16x32_bf16 v[78:81], v[138:141], v[212:215], v[78:81]
	v_mfma_f32_16x16x32_bf16 v[74:77], v[146:149], v[212:215], v[74:77]
	v_mfma_f32_16x16x32_bf16 v[70:73], v[138:141], v[232:235], v[70:73]
	v_mfma_f32_16x16x32_bf16 v[66:69], v[146:149], v[232:235], v[66:69]

.Lwinskip_7:
	s_setprio 0
	s_barrier
	s_add_i32 s74, s74, 2
	s_add_u32 s72, s72, 0x100
	s_addc_u32 s73, s73, 0
	s_add_u32 s64, s64, 0x100
	s_addc_u32 s65, s65, 0
	s_cmp_gt_u32 s74, 13
	s_cbranch_scc0 .LBB0_403
	s_and_b64 vcc, exec, s[30:31]
	s_cbranch_vccz .LBB0_406
	s_barrier
